# stage-B schedule C: partner CU runs the overlapped final norm first (full tile, while the K-lo CU computes 46 K-tiles), then its 18 K-tiles and the partial hand-off
# baseline (speedup 1.0000x reference)
.Lp9_stage_b:
	s_mov_b32 s100, 10
	s_movk_i32 s91, 42
	s_movk_i32 s97, 43
	s_cmpk_lt_u32 s101, 0x80
	s_cbranch_scc0 .Lp9_hi
	s_mov_b32 s96, 1
	s_add_u32 s4, s78, 0x8000000
	s_addc_u32 s5, s79, 0
	s_add_i32 s98, s101, 0x200
	s_movk_i32 s99, 0x280
	s_branch .Lp9_body
.Lp9_hi:
	s_mov_b32 s96, 2
	v_writelane_b32 v255, s12, 20
	v_writelane_b32 v255, s13, 21
	v_writelane_b32 v255, s14, 22
	v_writelane_b32 v255, s15, 23
	v_writelane_b32 v255, s16, 24
	v_writelane_b32 v255, s17, 25
	v_writelane_b32 v255, s18, 26
	v_writelane_b32 v255, s19, 27
	v_writelane_b32 v255, s20, 28
	v_writelane_b32 v255, s21, 29
	v_writelane_b32 v255, s22, 30
	v_writelane_b32 v255, s23, 31
	v_writelane_b32 v255, s24, 32
	v_writelane_b32 v255, s25, 33
	v_writelane_b32 v255, s26, 34
	v_writelane_b32 v255, s27, 35
	v_writelane_b32 v255, s28, 36
	v_writelane_b32 v255, s29, 37
	v_writelane_b32 v255, s30, 38
	v_writelane_b32 v255, s31, 39
	s_branch .Lp10a

.Lw10d:
	v_readlane_b32 s2, v254, 6
	v_readlane_b32 s3, v254, 7
	v_and_b32_e32 v0, 63, v210
	v_readfirstlane_b32 s0, v210
	v_lshlrev_b32_e32 v1, 3, v0
	v_lshlrev_b32_e32 v2, 4, v0
	v_mov_b32_e32 v3, 0x3a800000
	v_mov_b32_e32 v121, 0x358637bd
	s_lshr_b32 s0, s0, 6
	global_load_dwordx4 v[4:7], v2, s[2:3]
	global_load_dwordx4 v[8:11], v2, s[2:3] offset:1024
	global_load_dwordx4 v[12:15], v2, s[2:3] offset:2048
	global_load_dwordx4 v[16:19], v2, s[2:3] offset:3072
	s_and_b32 s1, s101, 0x7f
	s_and_b32 s4, s1, 7
	s_lshr_b32 s5, s1, 4
	s_cmp_lt_u32 s4, 4
	s_cselect_b32 s4, 4, 0xff
	s_cmp_eq_u32 s5, s4
	s_cbranch_scc1 .Lp10a_done
	s_and_b32 s4, s1, 7
	s_mul_i32 s4, s4, 20
	s_lshr_b32 s5, s1, 3
	s_add_i32 s4, s4, s5
	s_lshl_b32 s4, s4, 8
	s_cmp_gt_u32 s0, 7
	s_cbranch_scc1 .Lp10a_done
	s_lshl_b32 s5, s0, 5
	s_add_i32 s4, s4, s5
	s_movk_i32 s10, 8
	s_lshl_b32 s5, s4, 11
	s_add_u32 s12, s78, s5
	s_addc_u32 s13, s79, 0
	s_add_u32 s12, s12, 0x2000000
	s_addc_u32 s13, s13, 0
	s_lshl_b32 s5, s4, 12
	s_add_u32 s14, s76, s5
	s_addc_u32 s15, s77, 0

.LBB0_965:
	s_cmp_eq_u32 s96, 4
	s_cbranch_scc1 .Lp9_hi_store
	s_cmp_eq_u32 s96, 1
	s_cbranch_scc0 .Lp9_epi
	s_nop 7
	s_nop 7
	s_nop 7
	s_sub_i32 s32, s98, 0x200
	v_cmp_eq_u32_e32 vcc, 0, v210
	s_and_saveexec_b64 s[84:85], vcc
	s_cbranch_execz .Lp9_lo_pd
	s_lshl_b32 s86, s32, 2
	s_add_i32 s86, s86, 0x1e03900
	v_mov_b32_e32 v82, s86

.Lp9_to_seam9:
	s_cmp_eq_u32 s96, 2
	s_cbranch_scc0 .Lp9_ts9
	s_mov_b32 s96, 4
	s_movk_i32 s91, 14
	s_movk_i32 s97, 15
	s_add_u32 s4, s78, 0x8001700
	s_addc_u32 s5, s79, 0
	s_add_u32 s74, s74, 0x1700
	s_addc_u32 s75, s75, 0
	s_add_i32 s98, s101, 0x180
	s_movk_i32 s99, 0x280
	v_readlane_b32 s12, v255, 20
	v_readlane_b32 s13, v255, 21
	v_readlane_b32 s14, v255, 22
	v_readlane_b32 s15, v255, 23
	v_readlane_b32 s16, v255, 24
	v_readlane_b32 s17, v255, 25
	v_readlane_b32 s18, v255, 26
	v_readlane_b32 s19, v255, 27
	v_readlane_b32 s20, v255, 28
	v_readlane_b32 s21, v255, 29
	v_readlane_b32 s22, v255, 30
	v_readlane_b32 s23, v255, 31
	v_readlane_b32 s24, v255, 32
	v_readlane_b32 s25, v255, 33
	v_readlane_b32 s26, v255, 34
	v_readlane_b32 s27, v255, 35
	v_readlane_b32 s28, v255, 36
	v_readlane_b32 s29, v255, 37
	v_readlane_b32 s30, v255, 38
	v_readlane_b32 s31, v255, 39
	s_waitcnt vmcnt(0)
	s_nop 3
	s_branch .Lp9_body
